# A loop: K tiles fetched into a conflict-free LDS layout (chunk ^ ((row&3)<<2 | (row>>2)&3)) so the ds_read_b128 K fragment reads are no longer 2-way bank conflicted
# speedup vs baseline: 1.0095x; 1.0073x over previous
; DEV void attn_a_item(const Params& P, int layer, int batch, int item, char* lds) {
;   const int tid = opaque_tid(), wid = tid >> 6, lane = tid & 63, r32 = lane & 31, hi = lane >> 5;
;   const int seqlen = batch ? 16384 : 4096;
;   const int head = 3 - (item >> 7), k_ = item & 127;
;   const int kk_ = batch ? k_ : (k_ >> 2), mid_ = batch ? 64 : 16;
;   const int qb = mid_ + ((kk_ & 1) ? -((kk_ + 1) >> 1) : (kk_ >> 1));
;   const int seq = batch ? 0 : (k_ & 3);
;   const long tok0 = (long)seq * 4096;
;   const int c = wid >> 2, wq = wid & 3;
;   const int qpos = qb * 128 + wq * 32 + r32;
;   char* V_lds = lds; char* K_lds = lds + 32768;
;   float* wsl = reinterpret_cast<float*>(lds + LDS_WS) + wid * 64;
;   const float lam = WS{P.ws}.consts()[layer * 1024 + 0], nMC = -WS{P.ws}.consts()[layer * 1024 + 1], lam_init = WS{P.ws}.consts()[layer * 1024 + 3];
;   const float nslope = -exp2f(-2.f * (float)(head + 1)) * LOG2E;
;   bf16x8 qr[4];
;   {
;     const u16* Qw = WS{P.ws}.QA() + (tok0 + qpos) * 512 + head * 128 + c * 64 + hi * 8;
; #pragma unroll
;     for (int ks = 0; ks < 4; ++ks) qr[ks] = *reinterpret_cast<const bf16x8*>(Qw + ks * 16);
;   }
;   const u16* Kh = WS{P.ws}.KA() + tok0 * 512 + head * 128;
;   const u16* Vh = WS{P.ws}.VA() + tok0 * 512 + head * 128;
;   int akoff[2], avoff[2], ldst[2];
; #pragma unroll
;   for (int i = 0; i < 2; ++i) {
;     const int p = (wid + 8 * i) * 1024 + lane * 16;
;     ldst[i] = p;
;     const int row = p >> 8, cB = (p & 255) ^ ((row & 7) << 4);
;     akoff[i] = row * 512 + (cB >> 1);
;     const int st = p >> 9, within = p & 511, kk = (st >> 2) * 8 + (within >> 6);
;     const int k = kk, col = (st & 3) * 32 + ((within & 63) >> 1);
;     avoff[i] = k * 512 + col;
;   }
;   const int vb0 = (int)(uintptr_t)V_lds + v_rd_base(lane);
;     ...
;   f32x16 o[4] = {f32x16{}, f32x16{}, f32x16{}, f32x16{}};
;   float lsum = 0.f;
;   const int NT = seqlen >> 6;
;   const int Dk = (int)fminf(160.f / -nslope, 1.0e6f);
;   const int jlo = max(0, (qb * 128 - Dk) >> 6), jhi = min(NT - 1, (qb * 128 + 127 + Dk) >> 6);
;   ALOAD(0, jlo * 64); asm volatile("s_waitcnt vmcnt(0)" ::: "memory"); __syncthreads();
; DEV void phase_attn(const Params& P, int layer, int batch, char* lds) {
;     ...
;   for (;;) {
;     if (threadIdx.x == 0) *qw = (int)__hip_atomic_fetch_add(ctr, 1u, __ATOMIC_RELAXED, __HIP_MEMORY_SCOPE_AGENT);
;     __syncthreads();
.LBB0_371:
	s_or_b64 exec, exec, s[2:3]
	s_add_i32 s2, 0, 0x207f0
	s_cmp_lg_u32 s2, -1
	s_cselect_b32 s2, s2, 0
	s_cselect_b32 s3, s21, 0
	v_mov_b32_e32 v0, s2
	v_mov_b32_e32 v1, s3
	s_waitcnt lgkmcnt(0)
	s_barrier
	flat_load_dword v0, v[0:1] sc0 sc1
	s_waitcnt vmcnt(0)
	s_mov_b64 s[2:3], -1
	s_waitcnt lgkmcnt(0)
	s_barrier
	v_readfirstlane_b32 s63, v0
	s_cmpk_gt_i32 s63, 0x2ff
	s_cbranch_scc1 .LBB0_368
	s_cmpk_gt_i32 s63, 0xff
	s_cbranch_scc0 .LBB0_390
	s_add_i32 s22, s63, 0xffffff00
	s_and_b32 s18, s63, 0x7f
	s_bfe_u32 s19, s63, 0x50002
	s_and_b64 s[2:3], s[26:27], exec
	s_cselect_b32 s2, s19, s18
	s_add_i32 s18, s2, 1
	s_lshr_b32 s18, s18, 1
	s_and_b32 s3, s2, 1
	s_sub_i32 s18, 0, s18
	s_lshr_b32 s2, s2, 1
	s_cmp_eq_u32 s3, 0
	s_cselect_b32 s2, s2, s18
	v_readlane_b32 s3, v254, 32
	v_mov_b32_e32 v159, v226
	s_add_i32 s24, s2, s3
	s_lshl_b32 s2, s22, 12
	s_and_b32 s18, s2, 0x3000
	v_ashrrev_i32_e32 v4, 6, v159
	s_and_b64 s[2:3], s[26:27], exec
	v_lshlrev_b32_e32 v161, 5, v4
	v_and_b32_e32 v162, 31, v159
	s_cselect_b32 s19, 0, 0
	s_cselect_b32 s18, s18, 0
	s_lshl_b32 s64, s24, 7
	v_and_b32_e32 v163, 0x60, v161
	v_or3_b32 v0, v162, s64, v163
	s_lshr_b32 s2, s22, 6
	s_and_b32 s2, s2, 6
	v_ashrrev_i32_e32 v1, 31, v0
	s_or_b32 s2, s2, -8
	v_lshl_add_u64 v[0:1], s[18:19], 0, v[0:1]
	v_ashrrev_i32_e32 v164, 8, v159
	v_mov_b64_e32 v[2:3], s[8:9]
	v_ldexp_f32 v13, 1.0, s2
	v_lshlrev_b64 v[0:1], 10, v[0:1]
	s_andn2_b32 s2, 0x180, s22
	flat_load_dwordx2 v[128:129], v[2:3]
	flat_load_dword v158, v[2:3] offset:12
	v_lshl_add_u64 v[0:1], s[10:11], 0, v[0:1]
	s_lshl_b32 s22, s2, 1
	v_lshlrev_b32_e32 v2, 6, v164
	v_and_b32_e32 v165, 63, v159
	v_lshl_add_u64 v[0:1], v[0:1], 0, s[22:23]
	v_ashrrev_i32_e32 v3, 31, v2
	v_lshl_add_u64 v[0:1], v[2:3], 1, v[0:1]
	v_lshlrev_b32_e32 v6, 10, v4
	v_lshlrev_b32_e32 v3, 4, v165
	v_bfe_u32 v8, v159, 2, 3
	v_or_b32_e32 v166, v6, v3
	v_ashrrev_i32_e32 v4, 8, v6
	v_lshlrev_b32_e32 v11, 3, v165
	v_and_or_b32 v9, v4, s45, v8
	v_lshrrev_b32_e32 v5, 4, v166
	v_bfe_u32 v160, v159, 5, 1
	s_lshl_b32 s2, s18, 10
	v_and_b32_e32 v2, 24, v11
	v_and_b32_e32 v5, 0x60, v5
	v_lshlrev_b32_e32 v9, 9, v9
	v_lshlrev_b32_e32 v184, 4, v160
	s_add_u32 s24, s34, s2
	v_or3_b32 v14, v9, v5, v2
	v_add_u32_e32 v9, 0x2000, v6
	v_lshl_add_u64 v[0:1], v[0:1], 0, v[184:185]
	s_addc_u32 s25, s35, 0
	v_or_b32_e32 v15, v9, v3
	v_mul_f32_e32 v130, 0xbfb8aa3b, v13
	flat_load_dwordx4 v[96:99], v[0:1]
	flat_load_dwordx4 v[100:103], v[0:1] offset:32
	flat_load_dwordx4 v[104:107], v[0:1] offset:64
	flat_load_dwordx4 v[108:111], v[0:1] offset:96
	s_add_u32 s65, s36, s2
	v_ashrrev_i32_e32 v0, 8, v166
	v_ashrrev_i32_e32 v6, 8, v15
	v_div_scale_f32 v13, s[2:3], v130, v130, s46
	v_and_b32_e32 v7, 0xf0, v3
	v_lshlrev_b32_e32 v1, 4, v0
	v_lshlrev_b32_e32 v10, 4, v6
	v_rcp_f32_e32 v19, v13
	v_bitop3_b32 v1, v1, v7, s95 bitop3:0x6c
	v_bitop3_b32 v7, v10, v7, s95 bitop3:0x6c
	v_ashrrev_i32_e32 v10, 8, v9
	v_and_or_b32 v17, v10, s45, v8
	v_lshrrev_b32_e32 v15, 4, v15
	v_and_b32_e32 v15, 0x60, v15
	v_lshlrev_b32_e32 v17, 9, v17
	v_or3_b32 v18, v17, v15, v2
	v_fma_f32 v15, -v13, v19, 1.0
	v_fmac_f32_e32 v19, v15, v19
	v_div_scale_f32 v15, vcc, s46, v130, s46
	v_mul_f32_e32 v17, v15, v19
	v_fma_f32 v20, -v13, v17, v15
	v_fmac_f32_e32 v17, v20, v19
	v_fma_f32 v13, -v13, v17, v15
	v_div_fmas_f32 v13, v13, v19, v17
	v_div_fixup_f32 v13, v13, v130, s46
	v_min_f32_e32 v13, 0x49742400, v13
	v_cvt_i32_f32_e32 v13, v13
	s_addc_u32 s68, s38, 0
	s_add_u32 s3, s24, s22
	s_addc_u32 s71, s25, 0
	s_add_u32 s74, s65, s22
	v_readfirstlane_b32 s24, v13
	s_addc_u32 s75, s68, 0
	s_sub_i32 s2, s64, s24
	s_ashr_i32 s2, s2, 6
	s_or_b32 s65, s64, 0x7f
	s_max_i32 s2, s2, 0
	s_add_i32 s24, s65, s24
	s_ashr_i32 s78, s24, 6
	s_lshl_b32 s24, s2, 6
	s_mov_b32 s25, s23
	s_lshl_b64 s[68:69], s[24:25], 10
	v_lshlrev_b32_e32 v0, 9, v0
	v_lshrrev_b32_e32 v1, 1, v1
	s_add_u32 s70, s3, s68
	v_add_u32_e32 v20, 0, v166
	v_or_b32_e32 v12, v1, v0
	s_addc_u32 s71, s71, s69
	v_add_u32_e32 v15, 0x8000, v20
	s_add_u32 s68, s74, s68
	v_ashrrev_i32_e32 v13, 31, v12
	v_readfirstlane_b32 s3, v15
	v_lshlrev_b32_e32 v6, 9, v6
	v_lshrrev_b32_e32 v7, 1, v7
	s_addc_u32 s69, s75, s69
	v_lshl_add_u64 v[12:13], v[12:13], 1, s[70:71]
	s_mov_b32 m0, s3
	v_ashrrev_i32_e32 v15, 31, v14
	v_or_b32_e32 v16, v7, v6
	global_load_lds_dwordx4 v[12:13], off
	v_lshl_add_u64 v[12:13], v[14:15], 1, s[68:69]
	v_readfirstlane_b32 s3, v20
	v_add_u32_e32 v14, 0xa000, v20
	s_mov_b32 m0, s3
	v_ashrrev_i32_e32 v17, 31, v16
	v_readfirstlane_b32 s3, v14
	v_add_u32_e32 v14, 0x2000, v20
	global_load_lds_dwordx4 v[12:13], off
	v_lshl_add_u64 v[12:13], v[16:17], 1, s[70:71]
	s_mov_b32 m0, s3
	v_ashrrev_i32_e32 v19, 31, v18
	v_readfirstlane_b32 s3, v14
	global_load_lds_dwordx4 v[12:13], off
	v_lshl_add_u64 v[12:13], v[18:19], 1, s[68:69]
	s_mov_b32 m0, s3
	s_min_i32 s70, s49, s78
	global_load_lds_dwordx4 v[12:13], off
	s_waitcnt vmcnt(0)
	s_mov_b32 s25, 0
	s_cmp_gt_i32 s2, s70
	s_waitcnt vmcnt(0) lgkmcnt(0)
	s_barrier
	s_cbranch_scc1 .LBB0_382
; DEV int v_rd_base(int lane) { return ((lane & 3) << 3) | (((lane >> 2) & 3) << 6) | (((lane >> 4) & 1) << 5) | (((lane >> 5) & 1) << 8); }
; DEV void attn_a_item(const Params& P, int layer, int batch, int item, char* lds) {
;     ...
;   int akoff[2], avoff[2], ldst[2];
; #pragma unroll
;   for (int i = 0; i < 2; ++i) {
;     const int p = (wid + 8 * i) * 1024 + lane * 16;
;     ldst[i] = p;
;     const int row = p >> 8, cB = (p & 255) ^ ((row & 7) << 4);
;     akoff[i] = row * 512 + (cB >> 1);
;     const int st = p >> 9, within = p & 511, kk = (st >> 2) * 8 + (within >> 6);
;     const int k = kk, col = (st & 3) * 32 + ((within & 63) >> 1);
;     avoff[i] = k * 512 + col;
;   }
;   const int vb0 = (int)(uintptr_t)V_lds + v_rd_base(lane);
;     ...
;   f32x16 o[4] = {f32x16{}, f32x16{}, f32x16{}, f32x16{}};
;   float lsum = 0.f;
;   const int NT = seqlen >> 6;
;   const int Dk = (int)fminf(160.f / -nslope, 1.0e6f);
;     ...
;     for (int ks = 0; ks < 4; ++ks) {
;       const int cb = c * 128 + (ks * 16 + hi * 8) * 2;
;       kf[2 * ks] = *reinterpret_cast<const bf16x8*>(Ks + KSWZ(r32, cb));
;       kf[2 * ks + 1] = *reinterpret_cast<const bf16x8*>(Ks + KSWZ(32 + r32, cb));
;     }
	s_cmp_lg_u32 0, -1
	v_and_b32_e32 v13, 0xc0, v3
	s_cselect_b32 s3, 0, 0
	v_lshlrev_b32_e32 v12, 1, v165
	v_add_u32_e32 v13, s3, v13
	s_mov_b32 s3, s23
	v_and_b32_e32 v12, 32, v12
	v_and_b32_e32 v11, 0x118, v11
	s_lshl_b64 s[68:69], s[2:3], 16
	s_lshl_b64 s[74:75], s[18:19], 10
	v_add_u32_e32 v3, v9, v3
	v_add3_u32 v173, v13, v12, v11
	s_add_u32 s3, s68, s74
	v_lshlrev_b32_e32 v10, 9, v10
	v_lshlrev_b32_e32 v11, 9, v8
	s_movk_i32 s74, 0xf000
	v_lshrrev_b32_e32 v3, 4, v3
	v_and_or_b32 v8, v10, s74, v11
	v_and_b32_e32 v3, 0x60, v3
	v_or3_b32 v8, v8, v3, v2
	v_lshlrev_b32_e32 v3, 9, v4
	s_addc_u32 s71, s69, s75
	v_and_or_b32 v3, v3, s74, v11
	s_add_u32 s68, s55, s3
	v_or3_b32 v2, v3, v5, v2
	v_ashrrev_i32_e32 v9, 31, v8
	s_addc_u32 s69, s60, s71
	v_ashrrev_i32_e32 v3, 31, v2
	v_lshl_add_u64 v[150:151], v[8:9], 1, s[68:69]
	v_lshl_add_u64 v[152:153], v[2:3], 1, s[68:69]
	s_add_u32 s68, s61, s3
	v_add_u32_e32 v0, v1, v0
	v_lshlrev_b32_e32 v14, 2, v160
	s_addc_u32 s69, s62, s71
	v_ashrrev_i32_e32 v1, 31, v0
	v_lshlrev_b32_e32 v15, 7, v164
	v_lshlrev_b32_e32 v17, 4, v159
	v_add_u32_e32 v2, v7, v6
	v_lshl_add_u64 v[156:157], v[0:1], 1, s[68:69]
	v_sub_u32_e32 v0, v14, v162
	v_or_b32_e32 v16, v184, v15
	v_and_b32_e32 v17, 0x70, v17
	v_xor_b32_e32 v132, 0x80000000, v129
	v_ashrrev_i32_e32 v3, 31, v2
	v_sub_u32_e32 v0, v0, v163
	v_mov_b32_e32 v167, 0
	v_lshl_add_u32 v168, v162, 8, 0
	v_bitop3_b32 v169, v184, v17, v15 bitop3:0x36
	v_bitop3_b32 v170, v16, v17, 32 bitop3:0x36
	v_bitop3_b32 v171, v16, v17, 64 bitop3:0x36
	v_bitop3_b32 v172, v16, v17, s56 bitop3:0x36
	v_mov_b32_e32 v134, v130
	v_mov_b32_e32 v135, v130
	v_mov_b32_e32 v133, v132
	v_mov_b32_e32 v136, v132
	v_mov_b32_e32 v137, v132
	v_mov_b32_e32 v138, v132
	v_mov_b32_e32 v139, v132
	v_mov_b32_e32 v140, v132
	v_mov_b32_e32 v141, v132
	v_mov_b32_e32 v142, v132
	v_mov_b32_e32 v143, v132
	v_mov_b32_e32 v144, v132
	v_mov_b32_e32 v145, v132
	v_mov_b32_e32 v146, v132
	v_mov_b32_e32 v147, v132
	v_mov_b32_e32 v148, v132
	v_mov_b32_e32 v149, v132
	v_lshl_add_u64 v[154:155], v[2:3], 1, s[68:69]
	v_subrev_u32_e32 v174, s64, v0
	v_mov_b32_e32 v48, 0
	v_mov_b32_e32 v49, v167
	v_mov_b32_e32 v50, v167
	v_mov_b32_e32 v51, v167
	v_mov_b32_e32 v52, v167
	v_mov_b32_e32 v53, v167
	v_mov_b32_e32 v54, v167
	v_mov_b32_e32 v55, v167
	v_mov_b32_e32 v56, v167
	v_mov_b32_e32 v57, v167
	v_mov_b32_e32 v58, v167
	v_mov_b32_e32 v59, v167
	v_mov_b32_e32 v60, v167
	v_mov_b32_e32 v61, v167
	v_mov_b32_e32 v62, v167
	v_mov_b32_e32 v63, v167
	v_mov_b32_e32 v32, 0
	v_mov_b32_e32 v33, v167
	v_mov_b32_e32 v34, v167
	v_mov_b32_e32 v35, v167
	v_mov_b32_e32 v36, v167
	v_mov_b32_e32 v37, v167
	v_mov_b32_e32 v38, v167
	v_mov_b32_e32 v39, v167
	v_mov_b32_e32 v40, v167
	v_mov_b32_e32 v41, v167
	v_mov_b32_e32 v42, v167
	v_mov_b32_e32 v43, v167
	v_mov_b32_e32 v44, v167
	v_mov_b32_e32 v45, v167
	v_mov_b32_e32 v46, v167
	v_mov_b32_e32 v47, v167
	v_mov_b32_e32 v16, 0
	v_mov_b32_e32 v17, v167
	v_mov_b32_e32 v18, v167
	v_mov_b32_e32 v19, v167
	v_mov_b32_e32 v20, v167
	v_mov_b32_e32 v21, v167
	v_mov_b32_e32 v22, v167
	v_mov_b32_e32 v23, v167
	v_mov_b32_e32 v24, v167
	v_mov_b32_e32 v25, v167
	v_mov_b32_e32 v26, v167
	v_mov_b32_e32 v27, v167
	v_mov_b32_e32 v28, v167
	v_mov_b32_e32 v29, v167
	v_mov_b32_e32 v30, v167
	v_mov_b32_e32 v31, v167
	v_mov_b32_e32 v0, 0
	v_mov_b32_e32 v1, v167
	v_mov_b32_e32 v2, v167
	v_mov_b32_e32 v3, v167
	v_mov_b32_e32 v4, v167
	v_mov_b32_e32 v5, v167
	v_mov_b32_e32 v6, v167
	v_mov_b32_e32 v7, v167
	v_mov_b32_e32 v8, v167
	v_mov_b32_e32 v9, v167
	v_mov_b32_e32 v10, v167
	v_mov_b32_e32 v11, v167
	v_mov_b32_e32 v12, v167
	v_mov_b32_e32 v13, v167
	v_mov_b32_e32 v14, v167
	v_mov_b32_e32 v15, v167
	v_add_u32_e32 v186, v168, v169
	v_add_u32_e32 v187, v168, v170
	v_add_u32_e32 v188, v168, v171
	v_add_u32_e32 v189, v168, v172
	v_add_u32_e32 v186, 0x8000, v186
	v_add_u32_e32 v187, 0x8000, v187
	v_add_u32_e32 v188, 0x8000, v188
	v_add_u32_e32 v189, 0x8000, v189
	v_and_b32_e32 v218, 3, v162
	v_lshlrev_b32_e32 v218, 2, v218
	v_bfe_u32 v219, v162, 2, 2
	v_or_b32_e32 v218, v218, v219
	v_lshl_or_b32 v219, v164, 3, v160
	v_or_b32_e32 v220, 0, v219
	v_xor_b32_e32 v220, v220, v218
	v_lshl_add_u32 v169, v220, 4, v168
	v_add_u32_e32 v169, 0x8000, v169
; DEV int v_rd_base(int lane) { return ((lane & 3) << 3) | (((lane >> 2) & 3) << 6) | (((lane >> 4) & 1) << 5) | (((lane >> 5) & 1) << 8); }
; DEV void attn_a_item(const Params& P, int layer, int batch, int item, char* lds) {
;     ...
;   int akoff[2], avoff[2], ldst[2];
; #pragma unroll
;   for (int i = 0; i < 2; ++i) {
;     const int p = (wid + 8 * i) * 1024 + lane * 16;
;     ldst[i] = p;
;     const int row = p >> 8, cB = (p & 255) ^ ((row & 7) << 4);
;     akoff[i] = row * 512 + (cB >> 1);
;     const int st = p >> 9, within = p & 511, kk = (st >> 2) * 8 + (within >> 6);
;     const int k = kk, col = (st & 3) * 32 + ((within & 63) >> 1);
;     avoff[i] = k * 512 + col;
;   }
;   const int vb0 = (int)(uintptr_t)V_lds + v_rd_base(lane);
;     ...
;     const char* Ks = K_lds + bcur * 16384;
;     f32x16 p0, p1;
;     {
;       const float dbase = (float)(j * 64 - qpos + 4 * hi);
;       const int q0 = qb * 128;
;       if (j * 64 + 63 < q0 || j * 64 > q0 + 127) {
;         const float step = (j * 64 < q0) ? -nslope : nslope;
;         const float base = fmaf(dbase, step, nMC), step8 = 8.f * step;
;         p0[0] = base; p0[1] = base + step; p0[2] = fmaf(2.f, step, base); p0[3] = fmaf(3.f, step, base);
; #pragma unroll
;         for (int r = 4; r < 16; ++r) p0[r] = p0[r - 4] + step8;
; #pragma unroll
;         for (int r = 0; r < 4; ++r) p1[r] = p0[r + 12] + step8;
; #pragma unroll
;         for (int r = 4; r < 16; ++r) p1[r] = p1[r - 4] + step8;
;       } else {
;         float d0[16], d1[16];
;         d0[0] = dbase; d0[1] = dbase + 1.f; d0[2] = dbase + 2.f; d0[3] = d0[1] + 2.f;
; #pragma unroll
;         for (int r = 4; r < 16; ++r) d0[r] = d0[r - 4] + 8.f;
; #pragma unroll
;         for (int r = 0; r < 4; ++r) d1[r] = d0[r + 12] + 8.f;
; #pragma unroll
;         for (int r = 4; r < 16; ++r) d1[r] = d1[r - 4] + 8.f;
; #pragma unroll
;         for (int r = 0; r < 16; ++r) { p0[r] = fmaf(fabsf(d0[r]), nslope, nMC); p1[r] = fmaf(fabsf(d1[r]), nslope, nMC); }
;       }
;     }
;     const int vb = vb0 + bcur * 16384;
;     bf16x8 pa0, pa1, pa2, pa3;
;     s16x4 fa[8], fb[8];
;     bf16x8 kf[8];
; #pragma unroll
;     for (int ks = 0; ks < 4; ++ks) {
;       const int cb = c * 128 + (ks * 16 + hi * 8) * 2;
;       kf[2 * ks] = *reinterpret_cast<const bf16x8*>(Ks + KSWZ(r32, cb));
;       kf[2 * ks + 1] = *reinterpret_cast<const bf16x8*>(Ks + KSWZ(32 + r32, cb));
;     }
	v_or_b32_e32 v220, 2, v219
	v_xor_b32_e32 v220, v220, v218
	v_lshl_add_u32 v170, v220, 4, v168
	v_add_u32_e32 v170, 0x8000, v170
	v_or_b32_e32 v220, 4, v219
	v_xor_b32_e32 v220, v220, v218
	v_lshl_add_u32 v171, v220, 4, v168
	v_add_u32_e32 v171, 0x8000, v171
	v_or_b32_e32 v220, 6, v219
	v_xor_b32_e32 v220, v220, v218
	v_lshl_add_u32 v172, v220, 4, v168
	v_add_u32_e32 v172, 0x8000, v172
	v_readfirstlane_b32 s100, v166
	v_readfirstlane_b32 s25, v130
	v_cvt_f32_i32_e32 v166, v174
	s_nop 0
	v_mov_b32_e32 v112, v166
	v_add_f32_e32 v113, 0x3f800000, v166
	v_add_f32_e32 v114, 0x40000000, v166
	v_add_f32_e32 v115, 0x40400000, v166
	v_add_f32_e32 v116, 0x41000000, v166
	v_add_f32_e32 v117, 0x41100000, v166
	v_add_f32_e32 v118, 0x41200000, v166
	v_add_f32_e32 v119, 0x41300000, v166
	v_add_f32_e32 v120, 0x41800000, v166
	v_add_f32_e32 v121, 0x41880000, v166
	v_add_f32_e32 v122, 0x41900000, v166
	v_add_f32_e32 v123, 0x41980000, v166
	v_add_f32_e32 v124, 0x41c00000, v166
	v_add_f32_e32 v125, 0x41c80000, v166
	v_add_f32_e32 v126, 0x41d00000, v166
	v_add_f32_e32 v127, 0x41d80000, v166
	v_add_f32_e32 v133, 0x42000000, v166
	v_add_f32_e32 v134, 0x42040000, v166
	v_add_f32_e32 v135, 0x42080000, v166
	v_add_f32_e32 v136, 0x420c0000, v166
	v_add_f32_e32 v137, 0x42200000, v166
	v_add_f32_e32 v138, 0x42240000, v166
	v_add_f32_e32 v139, 0x42280000, v166
	v_add_f32_e32 v140, 0x422c0000, v166
	v_add_f32_e32 v141, 0x42400000, v166
	v_add_f32_e32 v142, 0x42440000, v166
	v_add_f32_e32 v143, 0x42480000, v166
	v_add_f32_e32 v144, 0x424c0000, v166
	v_add_f32_e32 v145, 0x42600000, v166
	v_add_f32_e32 v146, 0x42640000, v166
	v_add_f32_e32 v147, 0x42680000, v166
	v_add_f32_e32 v148, 0x426c0000, v166
	v_readfirstlane_b32 s71, v156
	v_readfirstlane_b32 s101, v157
	s_nop 3
	s_sub_u32 s71, s71, 0x1000
	s_subb_u32 s101, s101, 0
	v_subrev_u32_e32 v174, s71, v156
	v_subrev_u32_e32 v175, s71, v154
	s_add_u32 s68, s71, s22
	s_addc_u32 s69, s101, 0
	v_lshrrev_b32_e32 v221, 6, v159
	v_bfe_u32 v222, v165, 4, 2
	v_lshlrev_b32_e32 v222, 2, v222
	v_and_b32_e32 v223, 3, v221
	v_or_b32_e32 v222, v222, v223
	v_and_b32_e32 v223, 15, v165
	v_xor_b32_e32 v223, v223, v222
	v_lshrrev_b32_e32 v224, 4, v165
	v_lshlrev_b32_e32 v224, 10, v224
	v_lshl_add_u32 v224, v223, 4, v224
	v_and_b32_e32 v225, 1, v221
	v_lshlrev_b32_e32 v225, 6, v225
	v_sub_u32_e32 v224, v224, v225
	v_add_u32_e32 v174, 0x1000, v224
	v_add_u32_e32 v175, 0x8000, v174
	v_readfirstlane_b32 s71, v152
	v_readfirstlane_b32 s101, v153
	s_nop 3
	s_sub_u32 s71, s71, 0x1000
	s_subb_u32 s101, s101, 0
	v_subrev_u32_e32 v149, s71, v152
	v_subrev_u32_e32 v131, s71, v150
	s_add_u32 s74, s71, s22
	s_addc_u32 s75, s101, 0
	s_xor_b32 s65, s25, 0x80000000
	s_lshr_b32 s78, s64, 6
	v_mov_b32_e32 v154, 0
	v_mov_b32_e32 v155, 0
	v_mov_b32_e32 v156, 0
	v_mov_b32_e32 v157, 0
	v_mov_b32_e32 v202, 0
	v_mov_b32_e32 v203, 0
	v_mov_b32_e32 v204, 0
	v_mov_b32_e32 v205, 0
	v_mov_b32_e32 v206, 0
	v_mov_b32_e32 v207, 0
	v_mov_b32_e32 v208, 0
	v_mov_b32_e32 v209, 0
	v_mov_b32_e32 v210, 0
	v_mov_b32_e32 v211, 0
	v_mov_b32_e32 v212, 0
	v_mov_b32_e32 v213, 0
	v_mov_b32_e32 v214, 0
	v_mov_b32_e32 v215, 0
	v_mov_b32_e32 v216, 0
	v_mov_b32_e32 v217, 0
	s_cmp_lt_i32 s2, s78
	s_cselect_b32 s3, s65, s25
	s_sub_u32 s71, s2, s78
	s_cmp_lt_u32 s71, 2
	s_cselect_b64 vcc, -1, 0
	v_cvt_f32_i32_e32 v129, s24
	s_nop 0
	v_fma_f32 v168, v129, s3, v132
	ds_read_b128 v[218:221], v186 offset:0
	ds_read_b128 v[222:225], v187 offset:0
	ds_read_b128 v[232:235], v188 offset:0
	ds_read_b128 v[236:239], v189 offset:0
	ds_read_b128 v[240:243], v186 offset:8192
	ds_read_b128 v[244:247], v187 offset:8192
	ds_read_b128 v[248:251], v188 offset:8192
	ds_read_b128 v[194:197], v189 offset:8192
	s_cbranch_vccnz .Ldfa_diag_f_a
	v_fma_f32 v64, v112, s3, v168
	v_fma_f32 v65, v113, s3, v168
	v_fma_f32 v66, v114, s3, v168
	v_fma_f32 v67, v115, s3, v168
	v_fma_f32 v68, v116, s3, v168
	v_fma_f32 v69, v117, s3, v168
	v_fma_f32 v70, v118, s3, v168
	v_fma_f32 v71, v119, s3, v168
	v_fma_f32 v72, v120, s3, v168
	v_fma_f32 v73, v121, s3, v168
	v_fma_f32 v74, v122, s3, v168
	v_fma_f32 v75, v123, s3, v168
	v_fma_f32 v76, v124, s3, v168
	v_fma_f32 v77, v125, s3, v168
	v_fma_f32 v78, v126, s3, v168
	v_fma_f32 v79, v127, s3, v168
